# phase1 row loop rewritten: g hoisted, shift/scale once per row pair, next rows prefetched (ping-pong regs); plus dynamic Mcat queue
# speedup vs baseline: 1.0131x; 1.0024x over previous
.LBB0_171:
	global_load_dwordx4 v[112:115], v[28:29], off
	global_load_dwordx4 v[116:119], v[28:29], off offset:1024
	global_load_dwordx4 v[120:123], v[28:29], off offset:2048
	global_load_dwordx4 v[124:127], v[28:29], off offset:3072
	s_ashr_i32 s0, s4, 11
	s_mul_i32 s0, s0, 6
	s_lshl_b32 s0, s0, 12
	s_add_u32 s14, s90, s0
	s_addc_u32 s15, s91, 0
	s_add_u32 s16, s14, 0x1000
	s_addc_u32 s17, s15, 0
	global_load_dwordx4 v[48:51], v[32:33], off offset:-4096 nt
	global_load_dwordx4 v[52:55], v[32:33], off offset:-3072 nt
	global_load_dwordx4 v[56:59], v[32:33], off offset:-2048 nt
	global_load_dwordx4 v[60:63], v[32:33], off offset:-1024 nt
	global_load_dwordx4 v[64:67], v[32:33], off nt
	global_load_dwordx4 v[68:71], v[32:33], off offset:1024 nt
	global_load_dwordx4 v[72:75], v[32:33], off offset:2048 nt
	global_load_dwordx4 v[76:79], v[32:33], off offset:3072 nt
	global_load_dwordx4 v[128:131], v42, s[14:15]
	global_load_dwordx4 v[132:135], v42, s[14:15] offset:1024
	global_load_dwordx4 v[136:139], v42, s[14:15] offset:2048
	global_load_dwordx4 v[140:143], v42, s[14:15] offset:3072
	global_load_dwordx4 v[144:147], v42, s[16:17]
	global_load_dwordx4 v[148:151], v42, s[16:17] offset:1024
	global_load_dwordx4 v[152:155], v42, s[16:17] offset:2048
	global_load_dwordx4 v[156:159], v42, s[16:17] offset:3072
	s_waitcnt vmcnt(0)
.Lrms_loop:
	s_add_i32 s4, s4, s8
	s_min_i32 s5, s4, 0x7fff
	s_cmpk_gt_i32 s4, 0x7fff
	s_cselect_b32 s0, 0, s12
	s_cselect_b32 s1, 0, s13
	v_lshl_add_u64 v[32:33], v[32:33], 0, s[0:1]
	s_ashr_i32 s0, s5, 11
	s_mul_i32 s0, s0, 6
	s_lshl_b32 s0, s0, 12
	s_add_u32 s14, s90, s0
	s_addc_u32 s15, s91, 0
	s_add_u32 s16, s14, 0x1000
	s_addc_u32 s17, s15, 0
	global_load_dwordx4 v[80:83], v[32:33], off offset:-4096 nt
	global_load_dwordx4 v[84:87], v[32:33], off offset:-3072 nt
	global_load_dwordx4 v[88:91], v[32:33], off offset:-2048 nt
	global_load_dwordx4 v[92:95], v[32:33], off offset:-1024 nt
	global_load_dwordx4 v[96:99], v[32:33], off nt
	global_load_dwordx4 v[100:103], v[32:33], off offset:1024 nt
	global_load_dwordx4 v[104:107], v[32:33], off offset:2048 nt
	global_load_dwordx4 v[108:111], v[32:33], off offset:3072 nt
	global_load_dwordx4 v[160:163], v42, s[14:15]
	global_load_dwordx4 v[164:167], v42, s[14:15] offset:1024
	global_load_dwordx4 v[168:171], v42, s[14:15] offset:2048
	global_load_dwordx4 v[172:175], v42, s[14:15] offset:3072
	global_load_dwordx4 v[176:179], v42, s[16:17]
	global_load_dwordx4 v[180:183], v42, s[16:17] offset:1024
	global_load_dwordx4 v[184:187], v42, s[16:17] offset:2048
	global_load_dwordx4 v[188:191], v42, s[16:17] offset:3072
	s_waitcnt vmcnt(24)
	v_pk_mul_f32 v[0:1], v[48:49], v[48:49]
	v_pk_fma_f32 v[0:1], v[50:51], v[50:51], v[0:1]
	v_pk_fma_f32 v[0:1], v[52:53], v[52:53], v[0:1]
	v_pk_fma_f32 v[0:1], v[54:55], v[54:55], v[0:1]
	v_pk_fma_f32 v[0:1], v[56:57], v[56:57], v[0:1]
	v_pk_fma_f32 v[0:1], v[58:59], v[58:59], v[0:1]
	v_pk_fma_f32 v[0:1], v[60:61], v[60:61], v[0:1]
	v_pk_fma_f32 v[0:1], v[62:63], v[62:63], v[0:1]
	v_pk_mul_f32 v[2:3], v[64:65], v[64:65]
	v_pk_fma_f32 v[2:3], v[66:67], v[66:67], v[2:3]
	v_pk_fma_f32 v[2:3], v[68:69], v[68:69], v[2:3]
	v_pk_fma_f32 v[2:3], v[70:71], v[70:71], v[2:3]
	v_pk_fma_f32 v[2:3], v[72:73], v[72:73], v[2:3]
	v_pk_fma_f32 v[2:3], v[74:75], v[74:75], v[2:3]
	v_pk_fma_f32 v[2:3], v[76:77], v[76:77], v[2:3]
	v_pk_fma_f32 v[2:3], v[78:79], v[78:79], v[2:3]
	v_add_f32_e32 v0, v0, v1
	v_add_f32_e32 v2, v2, v3
	ds_bpermute_b32 v1, v34, v0
	ds_bpermute_b32 v3, v34, v2
	s_waitcnt lgkmcnt(0)
	v_add_f32_e32 v0, v0, v1
	v_add_f32_e32 v2, v2, v3
	ds_bpermute_b32 v1, v35, v0
	ds_bpermute_b32 v3, v35, v2
	s_waitcnt lgkmcnt(0)
	v_add_f32_e32 v0, v0, v1
	v_add_f32_e32 v2, v2, v3
	ds_bpermute_b32 v1, v36, v0
	ds_bpermute_b32 v3, v36, v2
	s_waitcnt lgkmcnt(0)
	v_add_f32_e32 v0, v0, v1
	v_add_f32_e32 v2, v2, v3
	ds_bpermute_b32 v1, v37, v0
	ds_bpermute_b32 v3, v37, v2
	s_waitcnt lgkmcnt(0)
	v_add_f32_e32 v0, v0, v1
	v_add_f32_e32 v2, v2, v3
	ds_bpermute_b32 v1, v38, v0
	ds_bpermute_b32 v3, v38, v2
	s_waitcnt lgkmcnt(0)
	v_add_f32_e32 v0, v0, v1
	v_add_f32_e32 v2, v2, v3
	ds_bpermute_b32 v1, v39, v0
	ds_bpermute_b32 v3, v39, v2
	s_waitcnt lgkmcnt(0)
	v_add_f32_e32 v0, v0, v1
	v_add_f32_e32 v2, v2, v3
	v_fmamk_f32 v0, v0, 0x3a800000, v40
	v_mul_f32_e32 v4, 0x4f800000, v0
	v_cmp_gt_f32_e32 vcc, s2, v0
	s_nop 1
	v_cndmask_b32_e32 v0, v0, v4, vcc
	v_sqrt_f32_e32 v4, v0
	s_nop 0
	v_add_u32_e32 v5, -1, v4
	v_add_u32_e32 v6, 1, v4
	v_fma_f32 v7, -v5, v4, v0
	v_fma_f32 v8, -v6, v4, v0
	v_cmp_ge_f32_e64 s[0:1], 0, v7
	s_nop 1
	v_cndmask_b32_e64 v4, v4, v5, s[0:1]
	v_cmp_lt_f32_e64 s[0:1], 0, v8
	s_nop 1
	v_cndmask_b32_e64 v4, v4, v6, s[0:1]
	v_mul_f32_e32 v5, 0x37800000, v4
	v_cndmask_b32_e32 v4, v4, v5, vcc
	v_cmp_class_f32_e32 vcc, v0, v41
	s_nop 1
	v_cndmask_b32_e32 v0, v4, v0, vcc
	v_div_scale_f32 v4, s[0:1], v0, v0, 1.0
	v_rcp_f32_e32 v6, v4
	v_div_scale_f32 v5, vcc, 1.0, v0, 1.0
	v_fma_f32 v7, -v4, v6, 1.0
	v_fmac_f32_e32 v6, v7, v6
	v_mul_f32_e32 v7, v5, v6
	v_fma_f32 v8, -v4, v7, v5
	v_fmac_f32_e32 v7, v8, v6
	v_fma_f32 v4, -v4, v7, v5
	v_div_fmas_f32 v4, v4, v6, v7
	v_div_fixup_f32 v0, v4, v0, 1.0
	v_fmamk_f32 v2, v2, 0x3a800000, v40
	v_mul_f32_e32 v10, 0x4f800000, v2
	v_cmp_gt_f32_e32 vcc, s2, v2
	s_nop 1
	v_cndmask_b32_e32 v2, v2, v10, vcc
	v_sqrt_f32_e32 v10, v2
	s_nop 0
	v_add_u32_e32 v11, -1, v10
	v_add_u32_e32 v12, 1, v10
	v_fma_f32 v13, -v11, v10, v2
	v_fma_f32 v14, -v12, v10, v2
	v_cmp_ge_f32_e64 s[0:1], 0, v13
	s_nop 1
	v_cndmask_b32_e64 v10, v10, v11, s[0:1]
	v_cmp_lt_f32_e64 s[0:1], 0, v14
	s_nop 1
	v_cndmask_b32_e64 v10, v10, v12, s[0:1]
	v_mul_f32_e32 v11, 0x37800000, v10
	v_cndmask_b32_e32 v10, v10, v11, vcc
	v_cmp_class_f32_e32 vcc, v2, v41
	s_nop 1
	v_cndmask_b32_e32 v2, v10, v2, vcc
	v_div_scale_f32 v10, s[0:1], v2, v2, 1.0
	v_rcp_f32_e32 v12, v10
	v_div_scale_f32 v11, vcc, 1.0, v2, 1.0
	v_fma_f32 v13, -v10, v12, 1.0
	v_fmac_f32_e32 v12, v13, v12
	v_mul_f32_e32 v13, v11, v12
	v_fma_f32 v14, -v10, v13, v11
	v_fmac_f32_e32 v13, v14, v12
	v_fma_f32 v10, -v10, v13, v11
	v_div_fmas_f32 v10, v10, v12, v13
	v_div_fixup_f32 v2, v10, v2, 1.0
	v_pk_add_f32 v[144:145], v[144:145], 1.0 op_sel_hi:[1,0]
	v_pk_add_f32 v[146:147], v[146:147], 1.0 op_sel_hi:[1,0]
	v_pk_add_f32 v[148:149], v[148:149], 1.0 op_sel_hi:[1,0]
	v_pk_add_f32 v[150:151], v[150:151], 1.0 op_sel_hi:[1,0]
	v_pk_add_f32 v[152:153], v[152:153], 1.0 op_sel_hi:[1,0]
	v_pk_add_f32 v[154:155], v[154:155], 1.0 op_sel_hi:[1,0]
	v_pk_add_f32 v[156:157], v[156:157], 1.0 op_sel_hi:[1,0]
	v_pk_add_f32 v[158:159], v[158:159], 1.0 op_sel_hi:[1,0]
	v_pk_mul_f32 v[48:49], v[48:49], v[0:1] op_sel_hi:[1,0]
	v_pk_mul_f32 v[50:51], v[50:51], v[0:1] op_sel_hi:[1,0]
	v_pk_mul_f32 v[48:49], v[112:113], v[48:49]
	v_pk_mul_f32 v[50:51], v[114:115], v[50:51]
	v_pk_fma_f32 v[48:49], v[144:145], v[48:49], v[128:129]
	v_pk_fma_f32 v[50:51], v[146:147], v[50:51], v[130:131]
	v_cvt_pk_bf16_f32 v48, v48, v49
	v_cvt_pk_bf16_f32 v49, v50, v51
	global_store_dwordx2 v[30:31], v[48:49], off offset:-3584
	v_pk_mul_f32 v[52:53], v[52:53], v[0:1] op_sel_hi:[1,0]
	v_pk_mul_f32 v[54:55], v[54:55], v[0:1] op_sel_hi:[1,0]
	v_pk_mul_f32 v[52:53], v[116:117], v[52:53]
	v_pk_mul_f32 v[54:55], v[118:119], v[54:55]
	v_pk_fma_f32 v[52:53], v[148:149], v[52:53], v[132:133]
	v_pk_fma_f32 v[54:55], v[150:151], v[54:55], v[134:135]
	v_cvt_pk_bf16_f32 v52, v52, v53
	v_cvt_pk_bf16_f32 v53, v54, v55
	global_store_dwordx2 v[30:31], v[52:53], off offset:-3072
	v_pk_mul_f32 v[56:57], v[56:57], v[0:1] op_sel_hi:[1,0]
	v_pk_mul_f32 v[58:59], v[58:59], v[0:1] op_sel_hi:[1,0]
	v_pk_mul_f32 v[56:57], v[120:121], v[56:57]
	v_pk_mul_f32 v[58:59], v[122:123], v[58:59]
	v_pk_fma_f32 v[56:57], v[152:153], v[56:57], v[136:137]
	v_pk_fma_f32 v[58:59], v[154:155], v[58:59], v[138:139]
	v_cvt_pk_bf16_f32 v56, v56, v57
	v_cvt_pk_bf16_f32 v57, v58, v59
	global_store_dwordx2 v[30:31], v[56:57], off offset:-2560
	v_pk_mul_f32 v[60:61], v[60:61], v[0:1] op_sel_hi:[1,0]
	v_pk_mul_f32 v[62:63], v[62:63], v[0:1] op_sel_hi:[1,0]
	v_pk_mul_f32 v[60:61], v[124:125], v[60:61]
	v_pk_mul_f32 v[62:63], v[126:127], v[62:63]
	v_pk_fma_f32 v[60:61], v[156:157], v[60:61], v[140:141]
	v_pk_fma_f32 v[62:63], v[158:159], v[62:63], v[142:143]
	v_cvt_pk_bf16_f32 v60, v60, v61
	v_cvt_pk_bf16_f32 v61, v62, v63
	global_store_dwordx2 v[30:31], v[60:61], off offset:-2048
	v_pk_mul_f32 v[64:65], v[64:65], v[2:3] op_sel_hi:[1,0]
	v_pk_mul_f32 v[66:67], v[66:67], v[2:3] op_sel_hi:[1,0]
	v_pk_mul_f32 v[64:65], v[112:113], v[64:65]
	v_pk_mul_f32 v[66:67], v[114:115], v[66:67]
	v_pk_fma_f32 v[64:65], v[144:145], v[64:65], v[128:129]
	v_pk_fma_f32 v[66:67], v[146:147], v[66:67], v[130:131]
	v_cvt_pk_bf16_f32 v64, v64, v65
	v_cvt_pk_bf16_f32 v65, v66, v67
	global_store_dwordx2 v[30:31], v[64:65], off offset:-1536
	v_pk_mul_f32 v[68:69], v[68:69], v[2:3] op_sel_hi:[1,0]
	v_pk_mul_f32 v[70:71], v[70:71], v[2:3] op_sel_hi:[1,0]
	v_pk_mul_f32 v[68:69], v[116:117], v[68:69]
	v_pk_mul_f32 v[70:71], v[118:119], v[70:71]
	v_pk_fma_f32 v[68:69], v[148:149], v[68:69], v[132:133]
	v_pk_fma_f32 v[70:71], v[150:151], v[70:71], v[134:135]
	v_cvt_pk_bf16_f32 v68, v68, v69
	v_cvt_pk_bf16_f32 v69, v70, v71
	global_store_dwordx2 v[30:31], v[68:69], off offset:-1024
	v_pk_mul_f32 v[72:73], v[72:73], v[2:3] op_sel_hi:[1,0]
	v_pk_mul_f32 v[74:75], v[74:75], v[2:3] op_sel_hi:[1,0]
	v_pk_mul_f32 v[72:73], v[120:121], v[72:73]
	v_pk_mul_f32 v[74:75], v[122:123], v[74:75]
	v_pk_fma_f32 v[72:73], v[152:153], v[72:73], v[136:137]
	v_pk_fma_f32 v[74:75], v[154:155], v[74:75], v[138:139]
	v_cvt_pk_bf16_f32 v72, v72, v73
	v_cvt_pk_bf16_f32 v73, v74, v75
	global_store_dwordx2 v[30:31], v[72:73], off offset:-512
	v_pk_mul_f32 v[76:77], v[76:77], v[2:3] op_sel_hi:[1,0]
	v_pk_mul_f32 v[78:79], v[78:79], v[2:3] op_sel_hi:[1,0]
	v_pk_mul_f32 v[76:77], v[124:125], v[76:77]
	v_pk_mul_f32 v[78:79], v[126:127], v[78:79]
	v_pk_fma_f32 v[76:77], v[156:157], v[76:77], v[140:141]
	v_pk_fma_f32 v[78:79], v[158:159], v[78:79], v[142:143]
	v_cvt_pk_bf16_f32 v76, v76, v77
	v_cvt_pk_bf16_f32 v77, v78, v79
	global_store_dwordx2 v[30:31], v[76:77], off
	v_lshl_add_u64 v[30:31], v[30:31], 0, s[10:11]
	s_cmpk_gt_i32 s4, 0x7fff
	s_cbranch_scc1 .Lrms_exit
	s_add_i32 s4, s4, s8
	s_min_i32 s5, s4, 0x7fff
	s_cmpk_gt_i32 s4, 0x7fff
	s_cselect_b32 s0, 0, s12
	s_cselect_b32 s1, 0, s13
	v_lshl_add_u64 v[32:33], v[32:33], 0, s[0:1]
	s_ashr_i32 s0, s5, 11
	s_mul_i32 s0, s0, 6
	s_lshl_b32 s0, s0, 12
	s_add_u32 s14, s90, s0
	s_addc_u32 s15, s91, 0
	s_add_u32 s16, s14, 0x1000
	s_addc_u32 s17, s15, 0
	global_load_dwordx4 v[48:51], v[32:33], off offset:-4096 nt
	global_load_dwordx4 v[52:55], v[32:33], off offset:-3072 nt
	global_load_dwordx4 v[56:59], v[32:33], off offset:-2048 nt
	global_load_dwordx4 v[60:63], v[32:33], off offset:-1024 nt
	global_load_dwordx4 v[64:67], v[32:33], off nt
	global_load_dwordx4 v[68:71], v[32:33], off offset:1024 nt
	global_load_dwordx4 v[72:75], v[32:33], off offset:2048 nt
	global_load_dwordx4 v[76:79], v[32:33], off offset:3072 nt
	global_load_dwordx4 v[128:131], v42, s[14:15]
	global_load_dwordx4 v[132:135], v42, s[14:15] offset:1024
	global_load_dwordx4 v[136:139], v42, s[14:15] offset:2048
	global_load_dwordx4 v[140:143], v42, s[14:15] offset:3072
	global_load_dwordx4 v[144:147], v42, s[16:17]
	global_load_dwordx4 v[148:151], v42, s[16:17] offset:1024
	global_load_dwordx4 v[152:155], v42, s[16:17] offset:2048
	global_load_dwordx4 v[156:159], v42, s[16:17] offset:3072
	s_waitcnt vmcnt(24)
	v_pk_mul_f32 v[0:1], v[80:81], v[80:81]
	v_pk_fma_f32 v[0:1], v[82:83], v[82:83], v[0:1]
	v_pk_fma_f32 v[0:1], v[84:85], v[84:85], v[0:1]
	v_pk_fma_f32 v[0:1], v[86:87], v[86:87], v[0:1]
	v_pk_fma_f32 v[0:1], v[88:89], v[88:89], v[0:1]
	v_pk_fma_f32 v[0:1], v[90:91], v[90:91], v[0:1]
	v_pk_fma_f32 v[0:1], v[92:93], v[92:93], v[0:1]
	v_pk_fma_f32 v[0:1], v[94:95], v[94:95], v[0:1]
	v_pk_mul_f32 v[2:3], v[96:97], v[96:97]
	v_pk_fma_f32 v[2:3], v[98:99], v[98:99], v[2:3]
	v_pk_fma_f32 v[2:3], v[100:101], v[100:101], v[2:3]
	v_pk_fma_f32 v[2:3], v[102:103], v[102:103], v[2:3]
	v_pk_fma_f32 v[2:3], v[104:105], v[104:105], v[2:3]
	v_pk_fma_f32 v[2:3], v[106:107], v[106:107], v[2:3]
	v_pk_fma_f32 v[2:3], v[108:109], v[108:109], v[2:3]
	v_pk_fma_f32 v[2:3], v[110:111], v[110:111], v[2:3]
	v_add_f32_e32 v0, v0, v1
	v_add_f32_e32 v2, v2, v3
	ds_bpermute_b32 v1, v34, v0
	ds_bpermute_b32 v3, v34, v2
	s_waitcnt lgkmcnt(0)
	v_add_f32_e32 v0, v0, v1
	v_add_f32_e32 v2, v2, v3
	ds_bpermute_b32 v1, v35, v0
	ds_bpermute_b32 v3, v35, v2
	s_waitcnt lgkmcnt(0)
	v_add_f32_e32 v0, v0, v1
	v_add_f32_e32 v2, v2, v3
	ds_bpermute_b32 v1, v36, v0
	ds_bpermute_b32 v3, v36, v2
	s_waitcnt lgkmcnt(0)
	v_add_f32_e32 v0, v0, v1
	v_add_f32_e32 v2, v2, v3
	ds_bpermute_b32 v1, v37, v0
	ds_bpermute_b32 v3, v37, v2
	s_waitcnt lgkmcnt(0)
	v_add_f32_e32 v0, v0, v1
	v_add_f32_e32 v2, v2, v3
	ds_bpermute_b32 v1, v38, v0
	ds_bpermute_b32 v3, v38, v2
	s_waitcnt lgkmcnt(0)
	v_add_f32_e32 v0, v0, v1
	v_add_f32_e32 v2, v2, v3
	ds_bpermute_b32 v1, v39, v0
	ds_bpermute_b32 v3, v39, v2
	s_waitcnt lgkmcnt(0)
	v_add_f32_e32 v0, v0, v1
	v_add_f32_e32 v2, v2, v3
	v_fmamk_f32 v0, v0, 0x3a800000, v40
	v_mul_f32_e32 v4, 0x4f800000, v0
	v_cmp_gt_f32_e32 vcc, s2, v0
	s_nop 1
	v_cndmask_b32_e32 v0, v0, v4, vcc
	v_sqrt_f32_e32 v4, v0
	s_nop 0
	v_add_u32_e32 v5, -1, v4
	v_add_u32_e32 v6, 1, v4
	v_fma_f32 v7, -v5, v4, v0
	v_fma_f32 v8, -v6, v4, v0
	v_cmp_ge_f32_e64 s[0:1], 0, v7
	s_nop 1
	v_cndmask_b32_e64 v4, v4, v5, s[0:1]
	v_cmp_lt_f32_e64 s[0:1], 0, v8
	s_nop 1
	v_cndmask_b32_e64 v4, v4, v6, s[0:1]
	v_mul_f32_e32 v5, 0x37800000, v4
	v_cndmask_b32_e32 v4, v4, v5, vcc
	v_cmp_class_f32_e32 vcc, v0, v41
	s_nop 1
	v_cndmask_b32_e32 v0, v4, v0, vcc
	v_div_scale_f32 v4, s[0:1], v0, v0, 1.0
	v_rcp_f32_e32 v6, v4
	v_div_scale_f32 v5, vcc, 1.0, v0, 1.0
	v_fma_f32 v7, -v4, v6, 1.0
	v_fmac_f32_e32 v6, v7, v6
	v_mul_f32_e32 v7, v5, v6
	v_fma_f32 v8, -v4, v7, v5
	v_fmac_f32_e32 v7, v8, v6
	v_fma_f32 v4, -v4, v7, v5
	v_div_fmas_f32 v4, v4, v6, v7
	v_div_fixup_f32 v0, v4, v0, 1.0
	v_fmamk_f32 v2, v2, 0x3a800000, v40
	v_mul_f32_e32 v10, 0x4f800000, v2
	v_cmp_gt_f32_e32 vcc, s2, v2
	s_nop 1
	v_cndmask_b32_e32 v2, v2, v10, vcc
	v_sqrt_f32_e32 v10, v2
	s_nop 0
	v_add_u32_e32 v11, -1, v10
	v_add_u32_e32 v12, 1, v10
	v_fma_f32 v13, -v11, v10, v2
	v_fma_f32 v14, -v12, v10, v2
	v_cmp_ge_f32_e64 s[0:1], 0, v13
	s_nop 1
	v_cndmask_b32_e64 v10, v10, v11, s[0:1]
	v_cmp_lt_f32_e64 s[0:1], 0, v14
	s_nop 1
	v_cndmask_b32_e64 v10, v10, v12, s[0:1]
	v_mul_f32_e32 v11, 0x37800000, v10
	v_cndmask_b32_e32 v10, v10, v11, vcc
	v_cmp_class_f32_e32 vcc, v2, v41
	s_nop 1
	v_cndmask_b32_e32 v2, v10, v2, vcc
	v_div_scale_f32 v10, s[0:1], v2, v2, 1.0
	v_rcp_f32_e32 v12, v10
	v_div_scale_f32 v11, vcc, 1.0, v2, 1.0
	v_fma_f32 v13, -v10, v12, 1.0
	v_fmac_f32_e32 v12, v13, v12
	v_mul_f32_e32 v13, v11, v12
	v_fma_f32 v14, -v10, v13, v11
	v_fmac_f32_e32 v13, v14, v12
	v_fma_f32 v10, -v10, v13, v11
	v_div_fmas_f32 v10, v10, v12, v13
	v_div_fixup_f32 v2, v10, v2, 1.0
	v_pk_add_f32 v[176:177], v[176:177], 1.0 op_sel_hi:[1,0]
	v_pk_add_f32 v[178:179], v[178:179], 1.0 op_sel_hi:[1,0]
	v_pk_add_f32 v[180:181], v[180:181], 1.0 op_sel_hi:[1,0]
	v_pk_add_f32 v[182:183], v[182:183], 1.0 op_sel_hi:[1,0]
	v_pk_add_f32 v[184:185], v[184:185], 1.0 op_sel_hi:[1,0]
	v_pk_add_f32 v[186:187], v[186:187], 1.0 op_sel_hi:[1,0]
	v_pk_add_f32 v[188:189], v[188:189], 1.0 op_sel_hi:[1,0]
	v_pk_add_f32 v[190:191], v[190:191], 1.0 op_sel_hi:[1,0]
	v_pk_mul_f32 v[80:81], v[80:81], v[0:1] op_sel_hi:[1,0]
	v_pk_mul_f32 v[82:83], v[82:83], v[0:1] op_sel_hi:[1,0]
	v_pk_mul_f32 v[80:81], v[112:113], v[80:81]
	v_pk_mul_f32 v[82:83], v[114:115], v[82:83]
	v_pk_fma_f32 v[80:81], v[176:177], v[80:81], v[160:161]
	v_pk_fma_f32 v[82:83], v[178:179], v[82:83], v[162:163]
	v_cvt_pk_bf16_f32 v80, v80, v81
	v_cvt_pk_bf16_f32 v81, v82, v83
	global_store_dwordx2 v[30:31], v[80:81], off offset:-3584
	v_pk_mul_f32 v[84:85], v[84:85], v[0:1] op_sel_hi:[1,0]
	v_pk_mul_f32 v[86:87], v[86:87], v[0:1] op_sel_hi:[1,0]
	v_pk_mul_f32 v[84:85], v[116:117], v[84:85]
	v_pk_mul_f32 v[86:87], v[118:119], v[86:87]
	v_pk_fma_f32 v[84:85], v[180:181], v[84:85], v[164:165]
	v_pk_fma_f32 v[86:87], v[182:183], v[86:87], v[166:167]
	v_cvt_pk_bf16_f32 v84, v84, v85
	v_cvt_pk_bf16_f32 v85, v86, v87
	global_store_dwordx2 v[30:31], v[84:85], off offset:-3072
	v_pk_mul_f32 v[88:89], v[88:89], v[0:1] op_sel_hi:[1,0]
	v_pk_mul_f32 v[90:91], v[90:91], v[0:1] op_sel_hi:[1,0]
	v_pk_mul_f32 v[88:89], v[120:121], v[88:89]
	v_pk_mul_f32 v[90:91], v[122:123], v[90:91]
	v_pk_fma_f32 v[88:89], v[184:185], v[88:89], v[168:169]
	v_pk_fma_f32 v[90:91], v[186:187], v[90:91], v[170:171]
	v_cvt_pk_bf16_f32 v88, v88, v89
	v_cvt_pk_bf16_f32 v89, v90, v91
	global_store_dwordx2 v[30:31], v[88:89], off offset:-2560
	v_pk_mul_f32 v[92:93], v[92:93], v[0:1] op_sel_hi:[1,0]
	v_pk_mul_f32 v[94:95], v[94:95], v[0:1] op_sel_hi:[1,0]
	v_pk_mul_f32 v[92:93], v[124:125], v[92:93]
	v_pk_mul_f32 v[94:95], v[126:127], v[94:95]
	v_pk_fma_f32 v[92:93], v[188:189], v[92:93], v[172:173]
	v_pk_fma_f32 v[94:95], v[190:191], v[94:95], v[174:175]
	v_cvt_pk_bf16_f32 v92, v92, v93
	v_cvt_pk_bf16_f32 v93, v94, v95
	global_store_dwordx2 v[30:31], v[92:93], off offset:-2048
	v_pk_mul_f32 v[96:97], v[96:97], v[2:3] op_sel_hi:[1,0]
	v_pk_mul_f32 v[98:99], v[98:99], v[2:3] op_sel_hi:[1,0]
	v_pk_mul_f32 v[96:97], v[112:113], v[96:97]
	v_pk_mul_f32 v[98:99], v[114:115], v[98:99]
	v_pk_fma_f32 v[96:97], v[176:177], v[96:97], v[160:161]
	v_pk_fma_f32 v[98:99], v[178:179], v[98:99], v[162:163]
	v_cvt_pk_bf16_f32 v96, v96, v97
	v_cvt_pk_bf16_f32 v97, v98, v99
	global_store_dwordx2 v[30:31], v[96:97], off offset:-1536
	v_pk_mul_f32 v[100:101], v[100:101], v[2:3] op_sel_hi:[1,0]
	v_pk_mul_f32 v[102:103], v[102:103], v[2:3] op_sel_hi:[1,0]
	v_pk_mul_f32 v[100:101], v[116:117], v[100:101]
	v_pk_mul_f32 v[102:103], v[118:119], v[102:103]
	v_pk_fma_f32 v[100:101], v[180:181], v[100:101], v[164:165]
	v_pk_fma_f32 v[102:103], v[182:183], v[102:103], v[166:167]
	v_cvt_pk_bf16_f32 v100, v100, v101
	v_cvt_pk_bf16_f32 v101, v102, v103
	global_store_dwordx2 v[30:31], v[100:101], off offset:-1024
	v_pk_mul_f32 v[104:105], v[104:105], v[2:3] op_sel_hi:[1,0]
	v_pk_mul_f32 v[106:107], v[106:107], v[2:3] op_sel_hi:[1,0]
	v_pk_mul_f32 v[104:105], v[120:121], v[104:105]
	v_pk_mul_f32 v[106:107], v[122:123], v[106:107]
	v_pk_fma_f32 v[104:105], v[184:185], v[104:105], v[168:169]
	v_pk_fma_f32 v[106:107], v[186:187], v[106:107], v[170:171]
	v_cvt_pk_bf16_f32 v104, v104, v105
	v_cvt_pk_bf16_f32 v105, v106, v107
	global_store_dwordx2 v[30:31], v[104:105], off offset:-512
	v_pk_mul_f32 v[108:109], v[108:109], v[2:3] op_sel_hi:[1,0]
	v_pk_mul_f32 v[110:111], v[110:111], v[2:3] op_sel_hi:[1,0]
	v_pk_mul_f32 v[108:109], v[124:125], v[108:109]
	v_pk_mul_f32 v[110:111], v[126:127], v[110:111]
	v_pk_fma_f32 v[108:109], v[188:189], v[108:109], v[172:173]
	v_pk_fma_f32 v[110:111], v[190:191], v[110:111], v[174:175]
	v_cvt_pk_bf16_f32 v108, v108, v109
	v_cvt_pk_bf16_f32 v109, v110, v111
	global_store_dwordx2 v[30:31], v[108:109], off
	v_lshl_add_u64 v[30:31], v[30:31], 0, s[10:11]
	s_cmpk_gt_i32 s4, 0x7fff
	s_cbranch_scc0 .Lrms_loop
.Lrms_exit:
	s_waitcnt vmcnt(0)
	v_and_b32_e32 v64, 63, v193
	s_lshl_b32 s71, s92, 8
	s_branch .Lmcat_setup
